# attention: packed v_pk_fma_f32 of the S-accumulator ALiBi bias init split into scalar v_fma_f32 (results feed the MFMA C operand)
# speedup vs baseline: 1.0027x; 1.0025x over previous
.LBB0_532:
	s_add_i32 s60, s84, s83
	s_add_i32 s56, s60, 0x7c0
	s_cmp_gt_i32 s56, s79
	s_cbranch_scc1 .LBB0_541
	v_add_u32_e32 v16, v206, v205
	ds_read_b128 v[4:7], v16
	ds_read_b128 v[8:11], v16 offset:32
	v_add3_u32 v2, s84, v220, 64
	v_cvt_f32_i32_e32 v2, v2
	s_andn2_b64 vcc, exec, s[58:59]
	v_fma_f32 v2, v190, v2, -v185
	v_fma_f32 v82, 0, v190, v2
	v_add_f32_e32 v83, v190, v2
	v_fma_f32 v84, v190, s16, v2
	v_fma_f32 v85, v191, s17, v2
	v_fma_f32 v86, v190, s18, v2
	v_fma_f32 v87, v191, s19, v2
	v_fma_f32 v88, v190, s20, v2
	v_fma_f32 v89, v191, s21, v2
	v_fma_f32 v90, v190, s22, v2
	v_fma_f32 v91, v191, s23, v2
	v_fma_f32 v92, v190, s24, v2
	v_fma_f32 v93, v191, s25, v2
	v_fma_f32 v94, v190, s36, v2
	v_fma_f32 v95, v191, s37, v2
	v_fma_f32 v96, v190, s54, v2
	v_fma_f32 v97, v191, s55, v2
	v_add_f32_e32 v2, v219, v2
	v_fma_f32 v98, 0, v190, v2
	s_waitcnt lgkmcnt(1)
	v_mfma_f32_32x32x16_bf16 v[82:97], v[4:7], v[114:117], v[82:97]
	v_add_f32_e32 v99, v190, v2
	v_fma_f32 v100, v190, s16, v2
	v_fma_f32 v101, v191, s17, v2
	v_fma_f32 v102, v190, s18, v2
	v_fma_f32 v103, v191, s19, v2
	v_fma_f32 v104, v190, s20, v2
	v_fma_f32 v105, v191, s21, v2
	v_fma_f32 v106, v190, s22, v2
	v_fma_f32 v107, v191, s23, v2
	v_fma_f32 v108, v190, s24, v2
	v_fma_f32 v109, v191, s25, v2
	v_fma_f32 v110, v190, s36, v2
	v_fma_f32 v111, v191, s37, v2
	s_waitcnt lgkmcnt(0)
	v_mfma_f32_32x32x16_bf16 v[82:97], v[8:11], v[118:121], v[82:97]
	ds_read_b128 v[4:7], v16 offset:64
	ds_read_b128 v[8:11], v16 offset:96
	v_fma_f32 v112, v190, s54, v2
	v_fma_f32 v113, v191, s55, v2
	s_waitcnt lgkmcnt(1)
	v_mfma_f32_32x32x16_bf16 v[82:97], v[4:7], v[122:125], v[82:97]
	ds_read_b128 v[4:7], v16 offset:8704
	ds_read_b128 v[12:15], v16 offset:8736
	s_waitcnt lgkmcnt(1)
	v_mfma_f32_32x32x16_bf16 v[98:113], v[4:7], v[114:117], v[98:113]
	s_waitcnt lgkmcnt(0)
	v_mfma_f32_32x32x16_bf16 v[98:113], v[12:15], v[118:121], v[98:113]
	v_mfma_f32_32x32x16_bf16 v[82:97], v[8:11], v[126:129], v[82:97]
	ds_read_b128 v[4:7], v16 offset:8768
	ds_read_b128 v[224:227], v16 offset:8800
	ds_read_b64_tr_b16 v[12:13], v207 offset:17408
	ds_read_b64_tr_b16 v[14:15], v207 offset:19968
	ds_read_b64_tr_b16 v[8:9], v207 offset:17472
	ds_read_b64_tr_b16 v[10:11], v207 offset:20032
	s_waitcnt lgkmcnt(5)
	v_mfma_f32_32x32x16_bf16 v[98:113], v[4:7], v[122:125], v[98:113]
	ds_read_b64_tr_b16 v[162:163], v207 offset:17536
	ds_read_b64_tr_b16 v[164:165], v207 offset:20096
	ds_read_b64_tr_b16 v[4:5], v207 offset:17600
	ds_read_b64_tr_b16 v[6:7], v207 offset:20160
	s_waitcnt lgkmcnt(8)
	v_mfma_f32_32x32x16_bf16 v[98:113], v[224:227], v[126:129], v[98:113]
	s_cbranch_vccnz .LBB0_535
	v_add_u32_e32 v2, s84, v222
	v_add_u32_e32 v17, 0x7e0, v2
	v_add_u32_e32 v16, 0x7c0, v2
	v_cmp_le_i32_e32 vcc, v17, v184
	s_nop 6
	v_cndmask_b32_e32 v98, v217, v98, vcc
	v_cmp_lt_i32_e32 vcc, v16, v184
	s_nop 1
	v_cndmask_b32_e32 v83, v217, v83, vcc
	v_cmp_le_i32_e32 vcc, v16, v184
	v_add_u32_e32 v16, 0x7e1, v2
	s_nop 0
	v_cndmask_b32_e32 v82, v217, v82, vcc
	v_cmp_le_i32_e32 vcc, v16, v184
	v_add_u32_e32 v16, 0x7c2, v2
	s_nop 0
	v_cndmask_b32_e32 v99, v217, v99, vcc
	v_cmp_le_i32_e32 vcc, v16, v184
	v_add_u32_e32 v16, 0x7e2, v2
	s_nop 0
	v_cndmask_b32_e32 v84, v217, v84, vcc
	v_cmp_le_i32_e32 vcc, v16, v184
	v_add_u32_e32 v16, 0x7c3, v2
	s_nop 0
	v_cndmask_b32_e32 v100, v217, v100, vcc
	v_cmp_le_i32_e32 vcc, v16, v184
	v_add_u32_e32 v16, 0x7e3, v2
	s_nop 0
	v_cndmask_b32_e32 v85, v217, v85, vcc
	v_cmp_le_i32_e32 vcc, v16, v184
	v_add_u32_e32 v16, 0x7c8, v2
	s_nop 0
	v_cndmask_b32_e32 v101, v217, v101, vcc
	v_cmp_le_i32_e32 vcc, v16, v184
	v_add_u32_e32 v16, 0x7e8, v2
	s_nop 0
	v_cndmask_b32_e32 v86, v217, v86, vcc
	v_cmp_le_i32_e32 vcc, v16, v184
	v_add_u32_e32 v16, 0x7c9, v2
	s_nop 0
	v_cndmask_b32_e32 v102, v217, v102, vcc
	v_cmp_le_i32_e32 vcc, v16, v184
	v_add_u32_e32 v16, 0x7e9, v2
	s_nop 0
	v_cndmask_b32_e32 v87, v217, v87, vcc
	v_cmp_le_i32_e32 vcc, v16, v184
	v_add_u32_e32 v16, 0x7ca, v2
	s_nop 0
	v_cndmask_b32_e32 v103, v217, v103, vcc
	v_cmp_le_i32_e32 vcc, v16, v184
	v_add_u32_e32 v16, 0x7ea, v2
	s_nop 0
	v_cndmask_b32_e32 v88, v217, v88, vcc
	v_cmp_le_i32_e32 vcc, v16, v184
	v_add_u32_e32 v16, 0x7cb, v2
	s_nop 0
	v_cndmask_b32_e32 v104, v217, v104, vcc
	v_cmp_le_i32_e32 vcc, v16, v184
	v_add_u32_e32 v16, 0x7eb, v2
	s_nop 0
	v_cndmask_b32_e32 v89, v217, v89, vcc
	v_cmp_le_i32_e32 vcc, v16, v184
	v_add_u32_e32 v16, 0x7d0, v2
	s_nop 0
	v_cndmask_b32_e32 v105, v217, v105, vcc
	v_cmp_le_i32_e32 vcc, v16, v184
	v_add_u32_e32 v16, 0x7f0, v2
	s_nop 0
	v_cndmask_b32_e32 v90, v217, v90, vcc
	v_cmp_le_i32_e32 vcc, v16, v184
	v_add_u32_e32 v16, 0x7d1, v2
	s_nop 0
	v_cndmask_b32_e32 v106, v217, v106, vcc
	v_cmp_le_i32_e32 vcc, v16, v184
	v_add_u32_e32 v16, 0x7f1, v2
	s_nop 0
	v_cndmask_b32_e32 v91, v217, v91, vcc
	v_cmp_le_i32_e32 vcc, v16, v184
	v_add_u32_e32 v16, 0x7d2, v2
	s_nop 0
	v_cndmask_b32_e32 v107, v217, v107, vcc
	v_cmp_le_i32_e32 vcc, v16, v184
	v_add_u32_e32 v16, 0x7f2, v2
	s_nop 0
	v_cndmask_b32_e32 v92, v217, v92, vcc
	v_cmp_le_i32_e32 vcc, v16, v184
	v_add_u32_e32 v16, 0x7d3, v2
	s_nop 0
	v_cndmask_b32_e32 v108, v217, v108, vcc
	v_cmp_le_i32_e32 vcc, v16, v184
	v_add_u32_e32 v16, 0x7f3, v2
	s_nop 0
	v_cndmask_b32_e32 v93, v217, v93, vcc
	v_cmp_le_i32_e32 vcc, v16, v184
	v_add_u32_e32 v16, 0x7d8, v2
	s_nop 0
	v_cndmask_b32_e32 v109, v217, v109, vcc
	v_cmp_le_i32_e32 vcc, v16, v184
	v_add_u32_e32 v16, 0x7f8, v2
	s_nop 0
	v_cndmask_b32_e32 v94, v217, v94, vcc
	v_cmp_le_i32_e32 vcc, v16, v184
	v_add_u32_e32 v16, 0x7d9, v2
	s_nop 0
	v_cndmask_b32_e32 v110, v217, v110, vcc
	v_cmp_le_i32_e32 vcc, v16, v184
	v_add_u32_e32 v16, 0x7f9, v2
	s_nop 0
	v_cndmask_b32_e32 v95, v217, v95, vcc
	v_cmp_le_i32_e32 vcc, v16, v184
	v_add_u32_e32 v16, 0x7da, v2
	s_nop 0
	v_cndmask_b32_e32 v111, v217, v111, vcc
	v_cmp_le_i32_e32 vcc, v16, v184
	v_add_u32_e32 v16, 0x7fa, v2
	s_nop 0
	v_cndmask_b32_e32 v96, v217, v96, vcc
	v_cmp_le_i32_e32 vcc, v16, v184
	v_add_u32_e32 v16, 0x7db, v2
	v_add_u32_e32 v2, 0x7fb, v2
	v_cndmask_b32_e32 v112, v217, v112, vcc
	v_cmp_le_i32_e32 vcc, v16, v184
	s_nop 1
	v_cndmask_b32_e32 v97, v217, v97, vcc
	v_cmp_le_i32_e32 vcc, v2, v184
	s_nop 1
	v_cndmask_b32_e32 v113, v217, v113, vcc

.LBB0_549:
	v_add_u32_e32 v16, v206, v205
	ds_read_b128 v[4:7], v16 offset:37888
	ds_read_b128 v[8:11], v16 offset:37920
	v_add_u32_e32 v2, s84, v220
	v_cvt_f32_i32_e32 v2, v2
	s_andn2_b64 vcc, exec, s[58:59]
	v_fma_f32 v2, v190, v2, -v185
	v_fma_f32 v82, 0, v190, v2
	v_add_f32_e32 v83, v190, v2
	v_fma_f32 v84, v190, s16, v2
	v_fma_f32 v85, v191, s17, v2
	v_fma_f32 v86, v190, s18, v2
	v_fma_f32 v87, v191, s19, v2
	v_fma_f32 v88, v190, s20, v2
	v_fma_f32 v89, v191, s21, v2
	v_fma_f32 v90, v190, s22, v2
	v_fma_f32 v91, v191, s23, v2
	v_fma_f32 v92, v190, s24, v2
	v_fma_f32 v93, v191, s25, v2
	v_fma_f32 v94, v190, s36, v2
	v_fma_f32 v95, v191, s37, v2
	v_fma_f32 v96, v190, s54, v2
	v_fma_f32 v97, v191, s55, v2
	v_add_f32_e32 v2, v219, v2
	v_fma_f32 v98, 0, v190, v2
	s_waitcnt lgkmcnt(1)
	v_mfma_f32_32x32x16_bf16 v[82:97], v[4:7], v[114:117], v[82:97]
	v_add_f32_e32 v99, v190, v2
	v_fma_f32 v100, v190, s16, v2
	v_fma_f32 v101, v191, s17, v2
	v_fma_f32 v102, v190, s18, v2
	v_fma_f32 v103, v191, s19, v2
	v_fma_f32 v104, v190, s20, v2
	v_fma_f32 v105, v191, s21, v2
	v_fma_f32 v106, v190, s22, v2
	v_fma_f32 v107, v191, s23, v2
	v_fma_f32 v108, v190, s24, v2
	v_fma_f32 v109, v191, s25, v2
	v_fma_f32 v110, v190, s36, v2
	v_fma_f32 v111, v191, s37, v2
	s_waitcnt lgkmcnt(0)
	v_mfma_f32_32x32x16_bf16 v[82:97], v[8:11], v[118:121], v[82:97]
	ds_read_b128 v[4:7], v16 offset:37952
	ds_read_b128 v[8:11], v16 offset:37984
	v_fma_f32 v112, v190, s54, v2
	v_fma_f32 v113, v191, s55, v2
	s_waitcnt lgkmcnt(1)
	v_mfma_f32_32x32x16_bf16 v[82:97], v[4:7], v[122:125], v[82:97]
	ds_read_b128 v[4:7], v16 offset:46592
	ds_read_b128 v[12:15], v16 offset:46624
	s_waitcnt lgkmcnt(1)
	v_mfma_f32_32x32x16_bf16 v[98:113], v[4:7], v[114:117], v[98:113]
	s_waitcnt lgkmcnt(0)
	v_mfma_f32_32x32x16_bf16 v[98:113], v[12:15], v[118:121], v[98:113]
	ds_read_b128 v[4:7], v16 offset:46656
	ds_read_b128 v[224:227], v16 offset:46688
	ds_read_b64_tr_b16 v[162:163], v210 offset:0
	ds_read_b64_tr_b16 v[164:165], v210 offset:2560
	ds_read_b64_tr_b16 v[12:13], v210 offset:64
	ds_read_b64_tr_b16 v[14:15], v210 offset:2624
	s_waitcnt lgkmcnt(5)
	v_mfma_f32_32x32x16_bf16 v[98:113], v[4:7], v[122:125], v[98:113]
	v_mfma_f32_32x32x16_bf16 v[82:97], v[8:11], v[126:129], v[82:97]
	ds_read_b64_tr_b16 v[8:9], v210 offset:128
	ds_read_b64_tr_b16 v[10:11], v210 offset:2688
	ds_read_b64_tr_b16 v[4:5], v210 offset:192
	ds_read_b64_tr_b16 v[6:7], v210 offset:2752
	s_waitcnt lgkmcnt(8)
	v_mfma_f32_32x32x16_bf16 v[98:113], v[224:227], v[126:129], v[98:113]
	s_cbranch_vccnz .LBB0_551
	v_add_u32_e32 v2, s84, v222
	v_add_u32_e32 v17, 0x7a0, v2
	v_add_u32_e32 v16, 0x780, v2
	v_cmp_le_i32_e32 vcc, v17, v184
	s_nop 6
	v_cndmask_b32_e32 v98, v217, v98, vcc
	v_cmp_lt_i32_e32 vcc, v16, v184
	s_nop 1
	v_cndmask_b32_e32 v83, v217, v83, vcc
	v_cmp_le_i32_e32 vcc, v16, v184
	v_add_u32_e32 v16, 0x7a1, v2
	s_nop 0
	v_cndmask_b32_e32 v82, v217, v82, vcc
	v_cmp_le_i32_e32 vcc, v16, v184
	v_add_u32_e32 v16, 0x782, v2
	s_nop 0
	v_cndmask_b32_e32 v99, v217, v99, vcc
	v_cmp_le_i32_e32 vcc, v16, v184
	v_add_u32_e32 v16, 0x7a2, v2
	s_nop 0
	v_cndmask_b32_e32 v84, v217, v84, vcc
	v_cmp_le_i32_e32 vcc, v16, v184
	v_add_u32_e32 v16, 0x783, v2
	s_nop 0
	v_cndmask_b32_e32 v100, v217, v100, vcc
	v_cmp_le_i32_e32 vcc, v16, v184
	v_add_u32_e32 v16, 0x7a3, v2
	s_nop 0
	v_cndmask_b32_e32 v85, v217, v85, vcc
	v_cmp_le_i32_e32 vcc, v16, v184
	v_add_u32_e32 v16, 0x788, v2
	s_nop 0
	v_cndmask_b32_e32 v101, v217, v101, vcc
	v_cmp_le_i32_e32 vcc, v16, v184
	v_add_u32_e32 v16, 0x7a8, v2
	s_nop 0
	v_cndmask_b32_e32 v86, v217, v86, vcc
	v_cmp_le_i32_e32 vcc, v16, v184
	v_add_u32_e32 v16, 0x789, v2
	s_nop 0
	v_cndmask_b32_e32 v102, v217, v102, vcc
	v_cmp_le_i32_e32 vcc, v16, v184
	v_add_u32_e32 v16, 0x7a9, v2
	s_nop 0
	v_cndmask_b32_e32 v87, v217, v87, vcc
	v_cmp_le_i32_e32 vcc, v16, v184
	v_add_u32_e32 v16, 0x78a, v2
	s_nop 0
	v_cndmask_b32_e32 v103, v217, v103, vcc
	v_cmp_le_i32_e32 vcc, v16, v184
	v_add_u32_e32 v16, 0x7aa, v2
	s_nop 0
	v_cndmask_b32_e32 v88, v217, v88, vcc
	v_cmp_le_i32_e32 vcc, v16, v184
	v_add_u32_e32 v16, 0x78b, v2
	s_nop 0
	v_cndmask_b32_e32 v104, v217, v104, vcc
	v_cmp_le_i32_e32 vcc, v16, v184
	v_add_u32_e32 v16, 0x7ab, v2
	s_nop 0
	v_cndmask_b32_e32 v89, v217, v89, vcc
	v_cmp_le_i32_e32 vcc, v16, v184
	v_add_u32_e32 v16, 0x790, v2
	s_nop 0
	v_cndmask_b32_e32 v105, v217, v105, vcc
	v_cmp_le_i32_e32 vcc, v16, v184
	v_add_u32_e32 v16, 0x7b0, v2
	s_nop 0
	v_cndmask_b32_e32 v90, v217, v90, vcc
	v_cmp_le_i32_e32 vcc, v16, v184
	v_add_u32_e32 v16, 0x791, v2
	s_nop 0
	v_cndmask_b32_e32 v106, v217, v106, vcc
	v_cmp_le_i32_e32 vcc, v16, v184
	v_add_u32_e32 v16, 0x7b1, v2
	s_nop 0
	v_cndmask_b32_e32 v91, v217, v91, vcc
	v_cmp_le_i32_e32 vcc, v16, v184
	v_add_u32_e32 v16, 0x792, v2
	s_nop 0
	v_cndmask_b32_e32 v107, v217, v107, vcc
	v_cmp_le_i32_e32 vcc, v16, v184
	v_add_u32_e32 v16, 0x7b2, v2
	s_nop 0
	v_cndmask_b32_e32 v92, v217, v92, vcc
	v_cmp_le_i32_e32 vcc, v16, v184
	v_add_u32_e32 v16, 0x793, v2
	s_nop 0
	v_cndmask_b32_e32 v108, v217, v108, vcc
	v_cmp_le_i32_e32 vcc, v16, v184
	v_add_u32_e32 v16, 0x7b3, v2
	s_nop 0
	v_cndmask_b32_e32 v93, v217, v93, vcc
	v_cmp_le_i32_e32 vcc, v16, v184
	v_add_u32_e32 v16, 0x798, v2
	s_nop 0
	v_cndmask_b32_e32 v109, v217, v109, vcc
	v_cmp_le_i32_e32 vcc, v16, v184
	v_add_u32_e32 v16, 0x7b8, v2
	s_nop 0
	v_cndmask_b32_e32 v94, v217, v94, vcc
	v_cmp_le_i32_e32 vcc, v16, v184
	v_add_u32_e32 v16, 0x799, v2
	s_nop 0
	v_cndmask_b32_e32 v110, v217, v110, vcc
	v_cmp_le_i32_e32 vcc, v16, v184
	v_add_u32_e32 v16, 0x7b9, v2
	s_nop 0
	v_cndmask_b32_e32 v95, v217, v95, vcc
	v_cmp_le_i32_e32 vcc, v16, v184
	v_add_u32_e32 v16, 0x79a, v2
	s_nop 0
	v_cndmask_b32_e32 v111, v217, v111, vcc
	v_cmp_le_i32_e32 vcc, v16, v184
	v_add_u32_e32 v16, 0x7ba, v2
	s_nop 0
	v_cndmask_b32_e32 v96, v217, v96, vcc
	v_cmp_le_i32_e32 vcc, v16, v184
	v_add_u32_e32 v16, 0x79b, v2
	v_add_u32_e32 v2, 0x7bb, v2
	v_cndmask_b32_e32 v112, v217, v112, vcc
	v_cmp_le_i32_e32 vcc, v16, v184
	s_nop 1
	v_cndmask_b32_e32 v97, v217, v97, vcc
	v_cmp_le_i32_e32 vcc, v2, v184
	s_nop 1
	v_cndmask_b32_e32 v113, v217, v113, vcc
